# plus P3 start stagger: workgroups 16..255 (which have a unit of slack in the branch-projection GEMMs) delay their start by ((bx>>4)&7) x ~4.5us so the epilogues' gate-load bursts do not all hit HBM to
# speedup vs baseline: 1.0068x; 1.0011x over previous
; #define PG8_STAGE(bufoff, gbase, voff) do { _Pragma("unroll") for (int _i = 0; _i < 2; ++_i) \
;         __builtin_amdgcn_global_load_lds((const unsigned*)((const char*)(gbase) + (voff)[_i]), (PG8_LAS unsigned*)(lds + (bufoff) + ldsw + _i * 8192), 16, 0, 0); } while (0)
; #define PG8_WAIT_V(n) asm volatile("s_waitcnt vmcnt(" #n ")" ::: "memory")
; #define PG8_BAR __builtin_amdgcn_s_barrier()
; template <class Epi, class Sched, bool ALIGN_EPI = false, bool SP2 = false>
; __device__ __forceinline__ void gemm_phase(PG8_LAS unsigned char* lds, const Gemm g, const Sched& S, const Epi& E) {
;     ...
;     const char* cA = (const char*)g.A + (size_t)cur.pm * tstepA + (size_t)cur.k0 * 2; const char* cB = (const char*)g.Bt + (size_t)cur.pn * tstepB + (size_t)cur.k0 * 2;
;     S.a_ready(cur);
;     if constexpr (SP2) {
;         PG8_STAGE(PG8_SB(0, 0), cB, voffB); PG8_STAGE(PG8_SB(0, 1), cB + hstepB, voffB); PG8_STAGE(PG8_SA(0, 0), cA, voffA); PG8_STAGE(PG8_SA(0, 1), cA + hstepA, voffA);
;         if (wr == 1) PG8_BAR;
;         PG8_WAIT_V(2); PG8_BAR;
;         PG8_STAGE(PG8_SB(1, 0), cB + kstep, voffB); PG8_STAGE(PG8_SA(1, 0), cA + kstep, voffA); PG8_STAGE(PG8_SB(1, 1), cB + hstepB + kstep, voffB);
;         PG8_WAIT_V(6); PG8_BAR;
;     } else {
;         PG8_STAGE(PG8_SB(0, 0), cB, voffB); PG8_STAGE(PG8_SA(0, 0), cA, voffA); PG8_STAGE(PG8_SB(0, 1), cB + hstepB, voffB); PG8_STAGE(PG8_SA(0, 1), cA + hstepA, voffA);
;         if (wr == 1) PG8_BAR;
;         PG8_WAIT_V(4); PG8_BAR;
;         PG8_STAGE(PG8_SB(1, 0), cB + kstep, voffB); PG8_STAGE(PG8_SA(1, 0), cA + kstep, voffA); PG8_STAGE(PG8_SB(1, 1), cB + hstepB + kstep, voffB);
;         PG8_WAIT_V(6); PG8_BAR;
.LBB0_914:
	s_cmp_lt_i32 s86, 4
	s_cselect_b64 s[4:5], -1, 0
	s_add_u32 s0, s84, 0x2aa00000
	s_addc_u32 s1, s85, 0
	s_and_b64 s[4:5], s[4:5], s[2:3]
	s_andn2_b64 vcc, exec, s[4:5]
	s_cbranch_vccnz .LBB0_943
	s_lshr_b32 s32, s68, 4
	s_cmp_eq_u32 s32, 0
	s_cbranch_scc1 .Lp3_nostag
	s_and_b32 s32, s32, 7
	s_cmp_eq_u32 s32, 0
	s_cbranch_scc1 .Lp3_nostag
.Lp3_stag:
	s_sleep 127
	s_sleep 20
	s_sub_u32 s32, s32, 1
	s_cmp_lg_u32 s32, 0
	s_cbranch_scc1 .Lp3_stag
.Lp3_nostag:
	v_lshrrev_b32_e32 v4, 5, v1
	v_lshrrev_b32_e32 v6, 1, v1
	v_and_b32_e32 v4, 4, v4
	v_bfe_u32 v5, v1, 2, 2
	v_and_b32_e32 v152, 24, v6
	v_lshlrev_b32_e32 v2, 4, v1
	s_waitcnt lgkmcnt(0)
	v_and_b32_e32 v3, 32, v1
	v_bfe_u32 v153, v1, 2, 4
	v_or3_b32 v4, v4, v5, v152
	v_lshrrev_b32_e32 v5, 3, v1
	s_movk_i32 s2, 0x70
	s_add_u32 s6, s84, 0x26800000
	v_bitop3_b32 v148, v2, v3, 48 bitop3:0x6c
	v_and_b32_e32 v149, 64, v1
	v_and_or_b32 v6, v5, s2, v153
	s_movk_i32 s2, 0x60
	v_add_u32_e32 v154, 0x2000, v2
	s_addc_u32 s7, s85, 0
	v_or_b32_e32 v3, v148, v149
	v_and_or_b32 v5, v5, s2, v4
	v_lshrrev_b32_e32 v2, 7, v154
	s_movk_i32 s2, 0xf0
	v_lshl_or_b32 v132, v5, 12, v3
	v_and_or_b32 v5, v2, s2, v153
	s_movk_i32 s2, 0xe0
	s_cmpk_lt_i32 s68, 0x210
	v_and_or_b32 v2, v2, s2, v4
	s_cselect_b64 s[8:9], -1, 0
	s_min_i32 s2, s68, 0x20f
	s_ashr_i32 s3, s2, 31
	s_lshr_b32 s3, s3, 29
	s_add_i32 s3, s2, s3
	s_ashr_i32 s10, s3, 3
	s_and_b32 s3, s3, -8
	s_sub_i32 s2, s2, s3
	s_ashr_i32 s26, s82, 31
	s_ashr_i32 s27, s68, 31
	s_cmp_lt_i32 s2, 0
	s_movk_i32 s3, 0x43
	s_cselect_b32 s3, s3, 0x42
	s_mul_i32 s2, s2, s3
	s_add_i32 s2, s2, s10
	s_ashr_i32 s3, s2, 31
	s_lshr_b32 s3, s3, 26
	s_add_i32 s3, s2, s3
	s_ashr_i32 s10, s3, 6
	v_lshl_or_b32 v130, v6, 12, v3
	v_lshl_or_b32 v134, v5, 12, v3
	v_lshl_or_b32 v136, v2, 12, v3
	v_lshlrev_b32_e32 v2, 6, v1
	v_lshlrev_b32_e32 v3, 2, v1
	s_lshl_b32 s36, s10, 3
	s_andn2_b32 s3, s3, 63
	v_lshlrev_b32_e32 v155, 1, v152
	v_and_b32_e32 v2, 0x3c0, v2
	v_and_b32_e32 v3, 32, v3
	s_sub_i32 s33, 0x42, s36
	s_sub_i32 s37, s2, s3
	v_mov_b32_e32 v133, 0
	v_and_b32_e32 v151, 15, v1
	v_bitop3_b32 v156, v155, v3, v2 bitop3:0x36
	s_cmpk_gt_i32 s68, 0x20f
	v_mov_b32_e32 v137, v133
	v_mov_b32_e32 v131, v133
	v_mov_b32_e32 v135, v133
	v_readfirstlane_b32 s3, v1
	s_cbranch_scc1 .LBB0_929
	s_min_u32 s12, s33, 8
	v_cvt_f32_ubyte0_e32 v3, s12
	v_cvt_f32_i32_e32 v2, s37
	v_rcp_iflag_f32_e32 v4, v3
	s_lshr_b32 s16, s3, 6
	s_ashr_i32 s2, s37, 30
	s_lshr_b32 s20, s3, 8
	v_mul_f32_e32 v4, v2, v4
	v_trunc_f32_e32 v4, v4
	v_fma_f32 v2, -v4, v3, v2
	v_cvt_i32_f32_e32 v4, v4
	s_lshl_b32 s38, s16, 10
	s_or_b32 s2, s2, 1
	v_cmp_ge_f32_e64 s[10:11], |v2|, v3
	s_and_b64 s[10:11], s[10:11], exec
	s_cselect_b32 s2, s2, 0
	v_readfirstlane_b32 s10, v4
	s_add_i32 s2, s10, s2
	s_mul_i32 s10, s2, s12
	s_sub_i32 s10, s37, s10
	s_sext_i32_i8 s10, s10
	s_add_i32 s10, s36, s10
	s_ashr_i32 s11, s10, 31
	s_bfe_i64 s[14:15], s[2:3], 0x80000
	s_lshl_b64 s[12:13], s[10:11], 20
	s_lshl_b64 s[14:15], s[14:15], 20
	s_add_u32 s14, s80, s14
	s_addc_u32 s15, s81, s15
	s_add_i32 s39, s38, 0
	s_add_i32 m0, s39, 0x10000
	v_lshl_add_u64 v[2:3], s[14:15], 0, v[132:133]
	global_load_lds_dwordx4 v[2:3], off
	s_add_i32 m0, s39, 0x12000
	s_add_u32 s18, s14, 0x80000
	v_lshl_add_u64 v[4:5], s[14:15], 0, v[136:137]
	s_addc_u32 s19, s15, 0
	global_load_lds_dwordx4 v[4:5], off
	s_add_i32 m0, s39, 0x14000
	v_lshl_add_u64 v[6:7], s[18:19], 0, v[132:133]
	global_load_lds_dwordx4 v[6:7], off
	s_add_i32 m0, s39, 0x16000
	v_lshl_add_u64 v[6:7], s[18:19], 0, v[136:137]
	s_add_u32 s18, s46, s12
	s_addc_u32 s19, s47, s13
	s_add_i32 s40, s39, 0x2000
	global_load_lds_dwordx4 v[6:7], off
	v_lshl_add_u64 v[8:9], s[18:19], 0, v[130:131]
	s_mov_b32 m0, s39
	s_add_u32 s12, s18, 0x80000
	global_load_lds_dwordx4 v[8:9], off
	v_lshl_add_u64 v[6:7], s[18:19], 0, v[134:135]
	s_mov_b32 m0, s40
	s_addc_u32 s13, s19, 0
	s_add_i32 s41, s39, 0x4000
	global_load_lds_dwordx4 v[6:7], off
	v_lshl_add_u64 v[10:11], s[12:13], 0, v[130:131]
	s_mov_b32 m0, s41
	s_add_i32 s42, s39, 0x6000
	global_load_lds_dwordx4 v[10:11], off
	v_lshl_add_u64 v[10:11], s[12:13], 0, v[134:135]
	s_mov_b32 m0, s42
	s_cmp_eq_u32 s20, 1
	global_load_lds_dwordx4 v[10:11], off
	s_cselect_b64 s[12:13], -1, 0
	s_cmp_lg_u32 s20, 1
	s_cbranch_scc1 .LBB0_918
	s_barrier
